# v20 + 64-bit accumulator clears (64 v_mov_b64 instead of 127 v_mov_b32) at every GEMM unit boundary
# speedup vs baseline: 1.0054x; 1.0054x over previous
; template <class Epi, class Sched, bool ALIGN_EPI = false, bool SP2 = false>
; __device__ __forceinline__ void gemm_phase(PG8_LAS unsigned char* lds, const Gemm g, const Sched& S, const Epi& E) {
;     ...
;         const bool has_next = S.next(ui + 1, nxt);
;         const char* nA = has_next ? (const char*)g.A + (size_t)nxt.pm * tstep : cA; const char* nB = has_next ? (const char*)g.Bt + (size_t)nxt.pn * tstep : cB;
;         for (int t = 0; t < nt; t += 2) {
;     ...
; #pragma unroll
;         for (int a = 0; a < 2; ++a)
; #pragma unroll
;             for (int b = 0; b < 2; ++b)
; #pragma unroll
;                 for (int m = 0; m < 4; ++m)
; #pragma unroll
;                     for (int n = 0; n < 2; ++n) acc[a][b][m][n] = (f32x4){0.f, 0.f, 0.f, 0.f};
.LBB0_191:
	s_ashr_i32 s13, s12, 31
	s_lshl_b64 s[14:15], s[12:13], 19
	v_readlane_b32 s16, v241, 53
	v_readlane_b32 s17, v241, 54
	s_add_u32 s14, s16, s14
	s_addc_u32 s15, s17, s15
	s_and_b64 s[16:17], s[2:3], exec
	s_cselect_b32 s5, s15, s21
	s_cselect_b32 s13, s14, s20
	s_ashr_i32 s11, s10, 31
	s_lshl_b64 s[16:17], s[10:11], 19
	v_readlane_b32 s24, v241, 36
	v_readlane_b32 s25, v241, 37
	s_add_u32 s16, s24, s16
	s_addc_u32 s17, s25, s17
	s_and_b64 s[24:25], s[2:3], exec
	s_cselect_b32 s11, s17, s23
	s_cselect_b32 s19, s16, s22
	s_add_u32 s20, s20, 0x40080
	s_addc_u32 s21, s21, 0
	s_add_u32 s73, s22, 0x100
	v_mov_b32_e32 v2, 0
	s_addc_u32 s74, s23, 0
	s_mov_b32 s75, -2
	v_mov_b32_e32 v3, 0
	v_mov_b64_e32 v[4:5], 0
	v_mov_b64_e32 v[6:7], 0
	v_mov_b64_e32 v[8:9], 0
	v_mov_b64_e32 v[14:15], 0
	v_mov_b64_e32 v[16:17], 0
	v_mov_b64_e32 v[22:23], 0
	v_mov_b64_e32 v[24:25], 0
	v_mov_b64_e32 v[30:31], 0
	v_mov_b64_e32 v[32:33], 0
	v_mov_b64_e32 v[38:39], 0
	v_mov_b64_e32 v[40:41], 0
	v_mov_b64_e32 v[46:47], 0
	v_mov_b64_e32 v[48:49], 0
	v_mov_b64_e32 v[54:55], 0
	v_mov_b64_e32 v[56:57], 0
	v_mov_b64_e32 v[10:11], 0
	v_mov_b64_e32 v[12:13], 0
	v_mov_b64_e32 v[18:19], 0
	v_mov_b64_e32 v[20:21], 0
	v_mov_b64_e32 v[26:27], 0
	v_mov_b64_e32 v[28:29], 0
	v_mov_b64_e32 v[34:35], 0
	v_mov_b64_e32 v[36:37], 0
	v_mov_b64_e32 v[42:43], 0
	v_mov_b64_e32 v[44:45], 0
	v_mov_b64_e32 v[50:51], 0
	v_mov_b64_e32 v[52:53], 0
	v_mov_b64_e32 v[58:59], 0
	v_mov_b64_e32 v[60:61], 0
	v_mov_b64_e32 v[62:63], 0
	v_mov_b64_e32 v[64:65], 0
	v_mov_b64_e32 v[66:67], 0
	v_mov_b64_e32 v[68:69], 0
	v_mov_b64_e32 v[70:71], 0
	v_mov_b64_e32 v[72:73], 0
	v_mov_b64_e32 v[78:79], 0
	v_mov_b64_e32 v[80:81], 0
	v_mov_b64_e32 v[86:87], 0
	v_mov_b64_e32 v[88:89], 0
	v_mov_b64_e32 v[94:95], 0
	v_mov_b64_e32 v[96:97], 0
	v_mov_b64_e32 v[102:103], 0
	v_mov_b64_e32 v[104:105], 0
	v_mov_b64_e32 v[110:111], 0
	v_mov_b64_e32 v[112:113], 0
	v_mov_b64_e32 v[118:119], 0
	v_mov_b64_e32 v[120:121], 0
	v_mov_b64_e32 v[74:75], 0
	v_mov_b64_e32 v[76:77], 0
	v_mov_b64_e32 v[82:83], 0
	v_mov_b64_e32 v[84:85], 0
	v_mov_b64_e32 v[90:91], 0
	v_mov_b64_e32 v[92:93], 0
	v_mov_b64_e32 v[98:99], 0
	v_mov_b64_e32 v[100:101], 0
	v_mov_b64_e32 v[106:107], 0
	v_mov_b64_e32 v[108:109], 0
	v_mov_b64_e32 v[114:115], 0
	v_mov_b64_e32 v[116:117], 0
	v_mov_b64_e32 v[122:123], 0
	v_mov_b64_e32 v[124:125], 0
	v_mov_b64_e32 v[126:127], 0
	v_mov_b64_e32 v[128:129], 0

; #define PG8_STAGE(bufoff, gbase, voff) do { _Pragma("unroll") for (int _i = 0; _i < 2; ++_i) \
;         __builtin_amdgcn_global_load_lds((const unsigned*)((const char*)(gbase) + (voff)[_i]), (PG8_LAS unsigned*)(lds + (bufoff) + ldsw + _i * 8192), 16, 0, 0); } while (0)
; #define PG8_LDA(dst, b, h) do { _Pragma("unroll") for (int m = 0; m < 4; ++m) _Pragma("unroll") for (int k = 0; k < 2; ++k) dst[m][k] = *(const PG8_LAS bf16x8*)(lds + PG8_SA(b, h) + aoff + m * 2048 + k * 1024); } while (0)
; #define PG8_LDB(dst, b, h) do { _Pragma("unroll") for (int n = 0; n < 2; ++n) _Pragma("unroll") for (int k = 0; k < 2; ++k) dst[n][k] = *(const PG8_LAS bf16x8*)(lds + PG8_SB(b, h) + boff + n * 2048 + k * 1024); } while (0)
; #define PG8_MMA(ai, bj, At, Bt) do { __builtin_amdgcn_s_setprio(1); _Pragma("unroll") for (int m = 0; m < 4; ++m) _Pragma("unroll") for (int n = 0; n < 2; ++n) _Pragma("unroll") for (int k = 0; k < 2; ++k) \
;         acc[ai][bj][m][n] = __builtin_amdgcn_mfma_f32_16x16x32_bf16(Bt[n][k], At[m][k], acc[ai][bj][m][n], 0, 0, 0); __builtin_amdgcn_s_setprio(0); } while (0)
; #define PG8_WAIT_V(n) asm volatile("s_waitcnt vmcnt(" #n ")" ::: "memory")
; #define PG8_WAIT_L(n) asm volatile("s_waitcnt lgkmcnt(" #n ")" ::: "memory")
; #define PG8_BAR __builtin_amdgcn_s_barrier()
; #define PG8_SCHED __builtin_amdgcn_sched_barrier(0)
; template <class Epi, class Sched, bool ALIGN_EPI = false, bool SP2 = false>
; __device__ __forceinline__ void gemm_phase(PG8_LAS unsigned char* lds, const Gemm g, const Sched& S, const Epi& E) {
;     ...
;             const bool last = (t == nt - 2);
;             const char* a1 = cA + (size_t)(t + 1) * kstep;
;             const char* a2 = last ? nA : cA + (size_t)(t + 2) * kstep; const char* b2 = last ? nB : cB + (size_t)(t + 2) * kstep;
;             const char* a3 = a2 + kstep; const char* b3 = b2 + kstep;
;             if (last && has_next) S.a_ready(nxt);
;             if constexpr (SP2) {
;             PG8_LDB(B0, 0, 0); PG8_LDB(B1, 0, 1); PG8_SCHED; PG8_LDA(At, 0, 0); PG8_STAGE(PG8_SA(1, 1), a1 + hstep, voffA);
;             PG8_WAIT_V(8); PG8_WAIT_L(0); PG8_BAR; PG8_MMA(0, 0, At, B0); PG8_MMA(0, 1, At, B1); PG8_BAR; PG8_SCHED;
;             PG8_LDA(At, 0, 1); PG8_STAGE(PG8_SB(0, 0), b2, voffB); PG8_STAGE(PG8_SB(0, 1), b2 + hstepB, voffB); PG8_STAGE(PG8_SA(0, 0), a2, voffA);
.LBB0_1180:
	v_add_u32_e32 v144, s55, v142
	ds_read_b128 v[154:157], v144
	ds_read_b128 v[158:161], v144 offset:1024
	ds_read_b128 v[162:165], v144 offset:2048
	ds_read_b128 v[166:169], v144 offset:3072
	v_add_u32_e32 v144, s56, v142
	s_add_u32 s34, s10, s28
	ds_read_b128 v[170:173], v144
	ds_read_b128 v[174:177], v144 offset:1024
	ds_read_b128 v[178:181], v144 offset:2048
	ds_read_b128 v[182:185], v144 offset:3072
	s_addc_u32 s35, s11, s29
	s_add_u32 s34, s34, 0x100
	s_addc_u32 s35, s35, 0
	s_add_u32 s61, s25, s28
	s_addc_u32 s62, s57, s29
	s_cmpk_eq_i32 s28, 0x700
	s_cselect_b32 s37, s21, s35
	s_cselect_b32 s36, s58, s34
	s_cselect_b32 s35, s19, s62
	s_cselect_b32 s34, s59, s61
	v_lshl_add_u64 v[144:145], v[138:139], 0, s[28:29]
	s_add_i32 m0, s39, 0xc000
	ds_read_b128 v[186:189], v143
	ds_read_b128 v[190:193], v143 offset:1024
	ds_read_b128 v[194:197], v143 offset:2048
	ds_read_b128 v[198:201], v143 offset:3072
	ds_read_b128 v[202:205], v143 offset:4096
	ds_read_b128 v[206:209], v143 offset:5120
	ds_read_b128 v[216:219], v143 offset:6144
	ds_read_b128 v[224:227], v143 offset:7168
	global_load_lds_dwordx4 v[144:145], off
	v_lshl_add_u64 v[144:145], v[140:141], 0, s[28:29]
	s_add_i32 m0, s39, 0xe000
	s_nop 0
	global_load_lds_dwordx4 v[144:145], off
	s_waitcnt vmcnt(8)
	s_waitcnt lgkmcnt(0)
	s_barrier
	v_mfma_f32_16x16x32_bf16 v[150:153], v[154:157], v[186:189], v[150:153]
	v_mfma_f32_16x16x32_bf16 v[144:147], v[162:165], v[186:189], v[146:149]
	v_mfma_f32_16x16x32_bf16 v[110:113], v[154:157], v[194:197], v[110:113]
	v_mfma_f32_16x16x32_bf16 v[106:109], v[162:165], v[194:197], v[106:109]
	v_mfma_f32_16x16x32_bf16 v[94:97], v[154:157], v[202:205], v[94:97]
	v_mfma_f32_16x16x32_bf16 v[90:93], v[162:165], v[202:205], v[90:93]
	v_mfma_f32_16x16x32_bf16 v[78:81], v[154:157], v[216:219], v[78:81]
	v_mfma_f32_16x16x32_bf16 v[74:77], v[162:165], v[216:219], v[74:77]
	v_mfma_f32_16x16x32_bf16 v[150:153], v[158:161], v[190:193], v[150:153]
	v_mfma_f32_16x16x32_bf16 v[144:147], v[166:169], v[190:193], v[144:147]
	v_mfma_f32_16x16x32_bf16 v[110:113], v[158:161], v[198:201], v[110:113]
	v_mfma_f32_16x16x32_bf16 v[106:109], v[166:169], v[198:201], v[106:109]
	v_mfma_f32_16x16x32_bf16 v[94:97], v[158:161], v[206:209], v[94:97]
	v_mfma_f32_16x16x32_bf16 v[90:93], v[166:169], v[206:209], v[90:93]
	v_mfma_f32_16x16x32_bf16 v[78:81], v[158:161], v[224:227], v[78:81]
	v_mfma_f32_16x16x32_bf16 v[74:77], v[166:169], v[224:227], v[74:77]
	v_mfma_f32_16x16x32_bf16 v[118:121], v[170:173], v[186:189], v[118:121]
	v_mfma_f32_16x16x32_bf16 v[114:117], v[178:181], v[186:189], v[114:117]
	v_mfma_f32_16x16x32_bf16 v[102:105], v[170:173], v[194:197], v[102:105]
	v_mfma_f32_16x16x32_bf16 v[98:101], v[178:181], v[194:197], v[98:101]
	v_mfma_f32_16x16x32_bf16 v[86:89], v[170:173], v[202:205], v[86:89]
	v_mfma_f32_16x16x32_bf16 v[82:85], v[178:181], v[202:205], v[82:85]
	v_mfma_f32_16x16x32_bf16 v[70:73], v[170:173], v[216:219], v[70:73]
	v_mfma_f32_16x16x32_bf16 v[66:69], v[178:181], v[216:219], v[66:69]
	v_mfma_f32_16x16x32_bf16 v[118:121], v[174:177], v[190:193], v[118:121]
	v_mfma_f32_16x16x32_bf16 v[114:117], v[182:185], v[190:193], v[114:117]
	v_mfma_f32_16x16x32_bf16 v[102:105], v[174:177], v[198:201], v[102:105]
	v_mfma_f32_16x16x32_bf16 v[98:101], v[182:185], v[198:201], v[98:101]
	v_mfma_f32_16x16x32_bf16 v[86:89], v[174:177], v[206:209], v[86:89]
	v_mfma_f32_16x16x32_bf16 v[82:85], v[182:185], v[206:209], v[82:85]
	v_mfma_f32_16x16x32_bf16 v[70:73], v[174:177], v[224:227], v[70:73]
	v_mfma_f32_16x16x32_bf16 v[66:69], v[182:185], v[224:227], v[66:69]
	s_barrier
	s_add_i32 s61, s55, s38
	v_lshl_add_u64 v[210:211], s[34:35], 0, v[124:125]
	s_mov_b32 m0, s61
	ds_read_b128 v[186:189], v143 offset:16384
	ds_read_b128 v[190:193], v143 offset:17408
	ds_read_b128 v[194:197], v143 offset:18432
	ds_read_b128 v[198:201], v143 offset:19456
	ds_read_b128 v[202:205], v143 offset:20480
	ds_read_b128 v[206:209], v143 offset:21504
	ds_read_b128 v[216:219], v143 offset:22528
	ds_read_b128 v[224:227], v143 offset:23552
	global_load_lds_dwordx4 v[210:211], off
	s_add_i32 m0, s61, 0x2000
	s_add_u32 s62, s34, 0x10000
	v_lshl_add_u64 v[220:221], s[34:35], 0, v[128:129]
	s_addc_u32 s63, s35, 0
	s_add_i32 s61, s56, s38
	global_load_lds_dwordx4 v[220:221], off
	v_lshl_add_u64 v[148:149], s[62:63], 0, v[124:125]
	s_mov_b32 m0, s61
	v_lshl_add_u64 v[228:229], s[36:37], 0, v[122:123]
	global_load_lds_dwordx4 v[148:149], off
	v_lshl_add_u64 v[148:149], s[62:63], 0, v[128:129]
	s_add_i32 m0, s61, 0x2000
	v_lshl_add_u64 v[230:231], s[36:37], 0, v[126:127]
	global_load_lds_dwordx4 v[148:149], off
	s_mov_b32 m0, s39
	s_nop 0
	global_load_lds_dwordx4 v[228:229], off
	s_mov_b32 m0, s42
	s_nop 0
	global_load_lds_dwordx4 v[230:231], off
	s_waitcnt vmcnt(8)
	s_waitcnt lgkmcnt(0)
	s_barrier
; #define PG8_STAGE(bufoff, gbase, voff) do { _Pragma("unroll") for (int _i = 0; _i < 2; ++_i) \
;         __builtin_amdgcn_global_load_lds((const unsigned*)((const char*)(gbase) + (voff)[_i]), (PG8_LAS unsigned*)(lds + (bufoff) + ldsw + _i * 8192), 16, 0, 0); } while (0)
; #define PG8_LDA(dst, b, h) do { _Pragma("unroll") for (int m = 0; m < 4; ++m) _Pragma("unroll") for (int k = 0; k < 2; ++k) dst[m][k] = *(const PG8_LAS bf16x8*)(lds + PG8_SA(b, h) + aoff + m * 2048 + k * 1024); } while (0)
; #define PG8_LDB(dst, b, h) do { _Pragma("unroll") for (int n = 0; n < 2; ++n) _Pragma("unroll") for (int k = 0; k < 2; ++k) dst[n][k] = *(const PG8_LAS bf16x8*)(lds + PG8_SB(b, h) + boff + n * 2048 + k * 1024); } while (0)
; #define PG8_MMA(ai, bj, At, Bt) do { __builtin_amdgcn_s_setprio(1); _Pragma("unroll") for (int m = 0; m < 4; ++m) _Pragma("unroll") for (int n = 0; n < 2; ++n) _Pragma("unroll") for (int k = 0; k < 2; ++k) \
;         acc[ai][bj][m][n] = __builtin_amdgcn_mfma_f32_16x16x32_bf16(Bt[n][k], At[m][k], acc[ai][bj][m][n], 0, 0, 0); __builtin_amdgcn_s_setprio(0); } while (0)
; #define PG8_WAIT_V(n) asm volatile("s_waitcnt vmcnt(" #n ")" ::: "memory")
; #define PG8_WAIT_L(n) asm volatile("s_waitcnt lgkmcnt(" #n ")" ::: "memory")
; #define PG8_BAR __builtin_amdgcn_s_barrier()
; #define PG8_SCHED __builtin_amdgcn_sched_barrier(0)
; template <class Epi, class Sched, bool ALIGN_EPI = false, bool SP2 = false>
; __device__ __forceinline__ void gemm_phase(PG8_LAS unsigned char* lds, const Gemm g, const Sched& S, const Epi& E) {
;     ...
;             PG8_WAIT_V(8); PG8_WAIT_L(0); PG8_BAR; PG8_MMA(1, 0, At, B0); PG8_MMA(1, 1, At, B1); PG8_BAR; PG8_SCHED;
;             PG8_LDB(B0, 1, 0); PG8_LDB(B1, 1, 1); PG8_SCHED; PG8_LDA(At, 1, 0); PG8_STAGE(PG8_SA(0, 1), a2 + hstep, voffA);
;             PG8_WAIT_V(8); PG8_WAIT_L(0); PG8_BAR; PG8_MMA(0, 0, At, B0); PG8_MMA(0, 1, At, B1); PG8_BAR; PG8_SCHED;
	v_mfma_f32_16x16x32_bf16 v[62:65], v[154:157], v[186:189], v[62:65]
	v_mfma_f32_16x16x32_bf16 v[58:61], v[162:165], v[186:189], v[58:61]
	v_mfma_f32_16x16x32_bf16 v[46:49], v[154:157], v[194:197], v[46:49]
	v_mfma_f32_16x16x32_bf16 v[42:45], v[162:165], v[194:197], v[42:45]
	v_mfma_f32_16x16x32_bf16 v[30:33], v[154:157], v[202:205], v[30:33]
	v_mfma_f32_16x16x32_bf16 v[26:29], v[162:165], v[202:205], v[26:29]
	v_mfma_f32_16x16x32_bf16 v[14:17], v[154:157], v[216:219], v[14:17]
	v_mfma_f32_16x16x32_bf16 v[10:13], v[162:165], v[216:219], v[10:13]
	v_mfma_f32_16x16x32_bf16 v[62:65], v[158:161], v[190:193], v[62:65]
	v_mfma_f32_16x16x32_bf16 v[58:61], v[166:169], v[190:193], v[58:61]
	v_mfma_f32_16x16x32_bf16 v[46:49], v[158:161], v[198:201], v[46:49]
	v_mfma_f32_16x16x32_bf16 v[42:45], v[166:169], v[198:201], v[42:45]
	v_mfma_f32_16x16x32_bf16 v[30:33], v[158:161], v[206:209], v[30:33]
	v_mfma_f32_16x16x32_bf16 v[26:29], v[166:169], v[206:209], v[26:29]
	v_mfma_f32_16x16x32_bf16 v[14:17], v[158:161], v[224:227], v[14:17]
	v_mfma_f32_16x16x32_bf16 v[10:13], v[166:169], v[224:227], v[10:13]
	v_mfma_f32_16x16x32_bf16 v[54:57], v[170:173], v[186:189], v[54:57]
	v_mfma_f32_16x16x32_bf16 v[50:53], v[178:181], v[186:189], v[50:53]
	v_mfma_f32_16x16x32_bf16 v[38:41], v[170:173], v[194:197], v[38:41]
	v_mfma_f32_16x16x32_bf16 v[34:37], v[178:181], v[194:197], v[34:37]
	v_mfma_f32_16x16x32_bf16 v[22:25], v[170:173], v[202:205], v[22:25]
	v_mfma_f32_16x16x32_bf16 v[18:21], v[178:181], v[202:205], v[18:21]
	v_mfma_f32_16x16x32_bf16 v[6:9], v[170:173], v[216:219], v[6:9]
	v_mfma_f32_16x16x32_bf16 v[2:5], v[178:181], v[216:219], v[2:5]
	v_mfma_f32_16x16x32_bf16 v[54:57], v[174:177], v[190:193], v[54:57]
	v_mfma_f32_16x16x32_bf16 v[50:53], v[182:185], v[190:193], v[50:53]
	v_mfma_f32_16x16x32_bf16 v[38:41], v[174:177], v[198:201], v[38:41]
	v_mfma_f32_16x16x32_bf16 v[34:37], v[182:185], v[198:201], v[34:37]
	v_mfma_f32_16x16x32_bf16 v[22:25], v[174:177], v[206:209], v[22:25]
	v_mfma_f32_16x16x32_bf16 v[18:21], v[182:185], v[206:209], v[18:21]
	v_mfma_f32_16x16x32_bf16 v[6:9], v[174:177], v[224:227], v[6:9]
	v_mfma_f32_16x16x32_bf16 v[2:5], v[182:185], v[224:227], v[2:5]
	s_barrier
	s_add_i32 s61, 0, 0x18000
	v_add_u32_e32 v148, s61, v142
	s_add_i32 s62, 0, 0x1c000
	ds_read_b128 v[154:157], v148
	ds_read_b128 v[158:161], v148 offset:1024
	ds_read_b128 v[162:165], v148 offset:2048
	ds_read_b128 v[166:169], v148 offset:3072
	v_add_u32_e32 v148, s62, v142
	ds_read_b128 v[170:173], v148
	ds_read_b128 v[174:177], v148 offset:1024
	ds_read_b128 v[178:181], v148 offset:2048
	ds_read_b128 v[182:185], v148 offset:3072
	s_add_u32 s36, s36, 0x40000
	s_addc_u32 s37, s37, 0
	s_mov_b32 m0, s44
	v_lshl_add_u64 v[148:149], s[36:37], 0, v[122:123]
	ds_read_b128 v[186:189], v143 offset:32768
	ds_read_b128 v[190:193], v143 offset:33792
	ds_read_b128 v[194:197], v143 offset:34816
	ds_read_b128 v[198:201], v143 offset:35840
	ds_read_b128 v[202:205], v143 offset:36864
	ds_read_b128 v[206:209], v143 offset:37888
	ds_read_b128 v[216:219], v143 offset:38912
	ds_read_b128 v[224:227], v143 offset:39936
	global_load_lds_dwordx4 v[148:149], off
	v_lshl_add_u64 v[148:149], s[36:37], 0, v[126:127]
	s_mov_b32 m0, s45
	s_nop 0
	global_load_lds_dwordx4 v[148:149], off
	s_waitcnt vmcnt(8)
	s_waitcnt lgkmcnt(0)
	s_barrier
	v_mfma_f32_16x16x32_bf16 v[148:151], v[154:157], v[186:189], v[150:153]
	v_mfma_f32_16x16x32_bf16 v[144:147], v[162:165], v[186:189], v[144:147]
	v_mfma_f32_16x16x32_bf16 v[110:113], v[154:157], v[194:197], v[110:113]
	v_mfma_f32_16x16x32_bf16 v[106:109], v[162:165], v[194:197], v[106:109]
	v_mfma_f32_16x16x32_bf16 v[94:97], v[154:157], v[202:205], v[94:97]
	v_mfma_f32_16x16x32_bf16 v[90:93], v[162:165], v[202:205], v[90:93]
	v_mfma_f32_16x16x32_bf16 v[78:81], v[154:157], v[216:219], v[78:81]
	v_mfma_f32_16x16x32_bf16 v[74:77], v[162:165], v[216:219], v[74:77]
	v_mfma_f32_16x16x32_bf16 v[150:153], v[158:161], v[190:193], v[148:151]
	v_mfma_f32_16x16x32_bf16 v[146:149], v[166:169], v[190:193], v[144:147]
	v_mfma_f32_16x16x32_bf16 v[110:113], v[158:161], v[198:201], v[110:113]
	v_mfma_f32_16x16x32_bf16 v[106:109], v[166:169], v[198:201], v[106:109]
	v_mfma_f32_16x16x32_bf16 v[94:97], v[158:161], v[206:209], v[94:97]
	v_mfma_f32_16x16x32_bf16 v[90:93], v[166:169], v[206:209], v[90:93]
	v_mfma_f32_16x16x32_bf16 v[78:81], v[158:161], v[224:227], v[78:81]
	v_mfma_f32_16x16x32_bf16 v[74:77], v[166:169], v[224:227], v[74:77]
	v_mfma_f32_16x16x32_bf16 v[118:121], v[170:173], v[186:189], v[118:121]
	v_mfma_f32_16x16x32_bf16 v[114:117], v[178:181], v[186:189], v[114:117]
	v_mfma_f32_16x16x32_bf16 v[102:105], v[170:173], v[194:197], v[102:105]
	v_mfma_f32_16x16x32_bf16 v[98:101], v[178:181], v[194:197], v[98:101]
	v_mfma_f32_16x16x32_bf16 v[86:89], v[170:173], v[202:205], v[86:89]
	v_mfma_f32_16x16x32_bf16 v[82:85], v[178:181], v[202:205], v[82:85]
	v_mfma_f32_16x16x32_bf16 v[70:73], v[170:173], v[216:219], v[70:73]
	v_mfma_f32_16x16x32_bf16 v[66:69], v[178:181], v[216:219], v[66:69]
	v_mfma_f32_16x16x32_bf16 v[118:121], v[174:177], v[190:193], v[118:121]
	v_mfma_f32_16x16x32_bf16 v[114:117], v[182:185], v[190:193], v[114:117]
	v_mfma_f32_16x16x32_bf16 v[102:105], v[174:177], v[198:201], v[102:105]
	v_mfma_f32_16x16x32_bf16 v[98:101], v[182:185], v[198:201], v[98:101]
	v_mfma_f32_16x16x32_bf16 v[86:89], v[174:177], v[206:209], v[86:89]
	v_mfma_f32_16x16x32_bf16 v[82:85], v[182:185], v[206:209], v[82:85]
	v_mfma_f32_16x16x32_bf16 v[70:73], v[174:177], v[224:227], v[70:73]
	v_mfma_f32_16x16x32_bf16 v[66:69], v[182:185], v[224:227], v[66:69]
	s_barrier
; #define PG8_STAGE(bufoff, gbase, voff) do { _Pragma("unroll") for (int _i = 0; _i < 2; ++_i) \
;         __builtin_amdgcn_global_load_lds((const unsigned*)((const char*)(gbase) + (voff)[_i]), (PG8_LAS unsigned*)(lds + (bufoff) + ldsw + _i * 8192), 16, 0, 0); } while (0)
; #define PG8_LDA(dst, b, h) do { _Pragma("unroll") for (int m = 0; m < 4; ++m) _Pragma("unroll") for (int k = 0; k < 2; ++k) dst[m][k] = *(const PG8_LAS bf16x8*)(lds + PG8_SA(b, h) + aoff + m * 2048 + k * 1024); } while (0)
; #define PG8_MMA(ai, bj, At, Bt) do { __builtin_amdgcn_s_setprio(1); _Pragma("unroll") for (int m = 0; m < 4; ++m) _Pragma("unroll") for (int n = 0; n < 2; ++n) _Pragma("unroll") for (int k = 0; k < 2; ++k) \
;         acc[ai][bj][m][n] = __builtin_amdgcn_mfma_f32_16x16x32_bf16(Bt[n][k], At[m][k], acc[ai][bj][m][n], 0, 0, 0); __builtin_amdgcn_s_setprio(0); } while (0)
; #define PG8_WAIT_V(n) asm volatile("s_waitcnt vmcnt(" #n ")" ::: "memory")
; #define PG8_WAIT_L(n) asm volatile("s_waitcnt lgkmcnt(" #n ")" ::: "memory")
; #define PG8_BAR __builtin_amdgcn_s_barrier()
; #define PG8_SCHED __builtin_amdgcn_sched_barrier(0)
; template <class Epi, class Sched, bool ALIGN_EPI = false, bool SP2 = false>
; __device__ __forceinline__ void gemm_phase(PG8_LAS unsigned char* lds, const Gemm g, const Sched& S, const Epi& E) {
;     ...
;             PG8_LDA(At, 1, 1); PG8_STAGE(PG8_SB(1, 0), b3, voffB); PG8_STAGE(PG8_SB(1, 1), b3 + hstepB, voffB); PG8_STAGE(PG8_SA(1, 0), a3, voffA);
;             PG8_WAIT_V(8); PG8_WAIT_L(0); PG8_BAR; PG8_MMA(1, 0, At, B0); PG8_MMA(1, 1, At, B1); PG8_BAR; PG8_SCHED;
;     ...
; #pragma unroll
;         for (int a = 0; a < 2; ++a)
; #pragma unroll
;             for (int b = 0; b < 2; ++b)
; #pragma unroll
;                 for (int m = 0; m < 4; ++m)
; #pragma unroll
;                     for (int n = 0; n < 2; ++n) acc[a][b][m][n] = (f32x4){0.f, 0.f, 0.f, 0.f};
	s_add_i32 s36, s61, s38
	v_lshl_add_u64 v[144:145], v[210:211], 0, s[16:17]
	s_mov_b32 m0, s36
	ds_read_b128 v[186:189], v143 offset:49152
	ds_read_b128 v[190:193], v143 offset:50176
	ds_read_b128 v[194:197], v143 offset:51200
	ds_read_b128 v[198:201], v143 offset:52224
	ds_read_b128 v[202:205], v143 offset:53248
	ds_read_b128 v[206:209], v143 offset:54272
	ds_read_b128 v[216:219], v143 offset:55296
	ds_read_b128 v[224:227], v143 offset:56320
	global_load_lds_dwordx4 v[144:145], off
	s_add_i32 m0, s36, 0x2000
	s_add_u32 s34, s34, 0x10080
	v_lshl_add_u64 v[144:145], v[220:221], 0, s[16:17]
	s_addc_u32 s35, s35, 0
	s_add_i32 s36, s62, s38
	global_load_lds_dwordx4 v[144:145], off
	v_lshl_add_u64 v[144:145], s[34:35], 0, v[124:125]
	s_mov_b32 m0, s36
	s_nop 0
	global_load_lds_dwordx4 v[144:145], off
	v_lshl_add_u64 v[144:145], s[34:35], 0, v[128:129]
	s_add_i32 m0, s36, 0x2000
	s_nop 0
	global_load_lds_dwordx4 v[144:145], off
	v_lshl_add_u64 v[144:145], v[228:229], 0, s[16:17]
	s_mov_b32 m0, s46
	s_nop 0
	global_load_lds_dwordx4 v[144:145], off
	v_lshl_add_u64 v[144:145], v[230:231], 0, s[16:17]
	s_mov_b32 m0, s47
	s_nop 0
	global_load_lds_dwordx4 v[144:145], off
	s_waitcnt vmcnt(8)
	s_waitcnt lgkmcnt(0)
	s_barrier
	v_mfma_f32_16x16x32_bf16 v[62:65], v[154:157], v[186:189], v[62:65]
	v_mfma_f32_16x16x32_bf16 v[58:61], v[162:165], v[186:189], v[58:61]
	v_mfma_f32_16x16x32_bf16 v[46:49], v[154:157], v[194:197], v[46:49]
	v_mfma_f32_16x16x32_bf16 v[42:45], v[162:165], v[194:197], v[42:45]
	v_mfma_f32_16x16x32_bf16 v[30:33], v[154:157], v[202:205], v[30:33]
	v_mfma_f32_16x16x32_bf16 v[26:29], v[162:165], v[202:205], v[26:29]
	v_mfma_f32_16x16x32_bf16 v[14:17], v[154:157], v[216:219], v[14:17]
	v_mfma_f32_16x16x32_bf16 v[10:13], v[162:165], v[216:219], v[10:13]
	v_mfma_f32_16x16x32_bf16 v[62:65], v[158:161], v[190:193], v[62:65]
	v_mfma_f32_16x16x32_bf16 v[58:61], v[166:169], v[190:193], v[58:61]
	v_mfma_f32_16x16x32_bf16 v[46:49], v[158:161], v[198:201], v[46:49]
	v_mfma_f32_16x16x32_bf16 v[42:45], v[166:169], v[198:201], v[42:45]
	v_mfma_f32_16x16x32_bf16 v[30:33], v[158:161], v[206:209], v[30:33]
	v_mfma_f32_16x16x32_bf16 v[26:29], v[166:169], v[206:209], v[26:29]
	v_mfma_f32_16x16x32_bf16 v[14:17], v[158:161], v[224:227], v[14:17]
	v_mfma_f32_16x16x32_bf16 v[10:13], v[166:169], v[224:227], v[10:13]
	v_mfma_f32_16x16x32_bf16 v[54:57], v[170:173], v[186:189], v[54:57]
	v_mfma_f32_16x16x32_bf16 v[50:53], v[178:181], v[186:189], v[50:53]
	v_mfma_f32_16x16x32_bf16 v[38:41], v[170:173], v[194:197], v[38:41]
	v_mfma_f32_16x16x32_bf16 v[34:37], v[178:181], v[194:197], v[34:37]
	v_mfma_f32_16x16x32_bf16 v[22:25], v[170:173], v[202:205], v[22:25]
	v_mfma_f32_16x16x32_bf16 v[18:21], v[178:181], v[202:205], v[18:21]
	v_mfma_f32_16x16x32_bf16 v[6:9], v[170:173], v[216:219], v[6:9]
	v_mfma_f32_16x16x32_bf16 v[2:5], v[178:181], v[216:219], v[2:5]
	v_mfma_f32_16x16x32_bf16 v[54:57], v[174:177], v[190:193], v[54:57]
	v_mfma_f32_16x16x32_bf16 v[50:53], v[182:185], v[190:193], v[50:53]
	v_mfma_f32_16x16x32_bf16 v[38:41], v[174:177], v[198:201], v[38:41]
	v_mfma_f32_16x16x32_bf16 v[34:37], v[182:185], v[198:201], v[34:37]
	v_mfma_f32_16x16x32_bf16 v[22:25], v[174:177], v[206:209], v[22:25]
	v_mfma_f32_16x16x32_bf16 v[18:21], v[182:185], v[206:209], v[18:21]
	v_mfma_f32_16x16x32_bf16 v[6:9], v[174:177], v[224:227], v[6:9]
	v_mfma_f32_16x16x32_bf16 v[2:5], v[182:185], v[224:227], v[2:5]
	s_barrier
	s_add_i32 s60, s60, 2
	s_add_u32 s28, s28, 0x100
	s_addc_u32 s29, s29, 0
	s_cmp_gt_u32 s60, 13
	s_cbranch_scc0 .LBB0_1180
	s_add_u32 s28, s25, 0xffffff00
	s_addc_u32 s29, s57, -1
	s_andn2_b64 vcc, exec, s[8:9]
	s_cbranch_vccnz .LBB0_1171
	v_mov_b32_e32 v2, 0
	s_mov_b32 s0, s18
	s_mov_b32 s14, s20
	s_mov_b64 s[10:11], s[26:27]
	s_mov_b32 s54, s24
	v_mov_b32_e32 v3, 0
	v_mov_b64_e32 v[4:5], 0
	v_mov_b64_e32 v[6:7], 0
	v_mov_b64_e32 v[8:9], 0
	v_mov_b64_e32 v[18:19], 0
	v_mov_b64_e32 v[20:21], 0
	v_mov_b64_e32 v[22:23], 0
	v_mov_b64_e32 v[24:25], 0
	v_mov_b64_e32 v[34:35], 0
	v_mov_b64_e32 v[36:37], 0
	v_mov_b64_e32 v[38:39], 0
	v_mov_b64_e32 v[40:41], 0
	v_mov_b64_e32 v[50:51], 0
	v_mov_b64_e32 v[52:53], 0
	v_mov_b64_e32 v[54:55], 0
	v_mov_b64_e32 v[56:57], 0
	v_mov_b64_e32 v[10:11], 0
	v_mov_b64_e32 v[12:13], 0
	v_mov_b64_e32 v[14:15], 0
	v_mov_b64_e32 v[16:17], 0
	v_mov_b64_e32 v[26:27], 0
	v_mov_b64_e32 v[28:29], 0
	v_mov_b64_e32 v[30:31], 0
	v_mov_b64_e32 v[32:33], 0
	v_mov_b64_e32 v[42:43], 0
	v_mov_b64_e32 v[44:45], 0
	v_mov_b64_e32 v[46:47], 0
	v_mov_b64_e32 v[48:49], 0
	v_mov_b64_e32 v[58:59], 0
	v_mov_b64_e32 v[60:61], 0
	v_mov_b64_e32 v[62:63], 0
	v_mov_b64_e32 v[64:65], 0
	v_mov_b64_e32 v[66:67], 0
	v_mov_b64_e32 v[68:69], 0
	v_mov_b64_e32 v[70:71], 0
	v_mov_b64_e32 v[72:73], 0
	v_mov_b64_e32 v[82:83], 0
	v_mov_b64_e32 v[84:85], 0
	v_mov_b64_e32 v[86:87], 0
	v_mov_b64_e32 v[88:89], 0
	v_mov_b64_e32 v[98:99], 0
	v_mov_b64_e32 v[100:101], 0
	v_mov_b64_e32 v[102:103], 0
	v_mov_b64_e32 v[104:105], 0
	v_mov_b64_e32 v[114:115], 0
	v_mov_b64_e32 v[116:117], 0
	v_mov_b64_e32 v[118:119], 0
	v_mov_b64_e32 v[120:121], 0
	v_mov_b64_e32 v[74:75], 0
	v_mov_b64_e32 v[76:77], 0
	v_mov_b64_e32 v[78:79], 0
	v_mov_b64_e32 v[80:81], 0
	v_mov_b64_e32 v[90:91], 0
	v_mov_b64_e32 v[92:93], 0
	v_mov_b64_e32 v[94:95], 0
	v_mov_b64_e32 v[96:97], 0
	v_mov_b64_e32 v[106:107], 0
	v_mov_b64_e32 v[108:109], 0
	v_mov_b64_e32 v[110:111], 0
	v_mov_b64_e32 v[112:113], 0
	v_mov_b64_e32 v[146:147], 0
	v_mov_b64_e32 v[148:149], 0
	v_mov_b64_e32 v[150:151], 0
	v_mov_b64_e32 v[152:153], 0
	s_andn2_b64 vcc, exec, s[6:7]
	s_cbranch_vccnz .LBB0_1172

; template <class Epi, class Sched, bool ALIGN_EPI = false, bool SP2 = false>
; __device__ __forceinline__ void gemm_phase(PG8_LAS unsigned char* lds, const Gemm g, const Sched& S, const Epi& E) {
;     ...
;         const bool has_next = S.next(ui + 1, nxt);
;         const char* nA = has_next ? (const char*)g.A + (size_t)nxt.pm * tstep : cA; const char* nB = has_next ? (const char*)g.Bt + (size_t)nxt.pn * tstep : cB;
;         for (int t = 0; t < nt; t += 2) {
;     ...
; #pragma unroll
;         for (int a = 0; a < 2; ++a)
; #pragma unroll
;             for (int b = 0; b < 2; ++b)
; #pragma unroll
;                 for (int m = 0; m < 4; ++m)
; #pragma unroll
;                     for (int n = 0; n < 2; ++n) acc[a][b][m][n] = (f32x4){0.f, 0.f, 0.f, 0.f};
.LBB0_1312:
	s_ashr_i32 s27, s26, 31
	s_lshl_b64 s[28:29], s[26:27], 19
	s_add_u32 s28, s12, s28
	s_addc_u32 s29, s13, s29
	s_and_b64 s[34:35], s[6:7], exec
	s_cselect_b32 s9, s29, s39
	s_cselect_b32 s27, s28, s38
	s_ashr_i32 s25, s24, 31
	s_lshl_b64 s[34:35], s[24:25], 19
	s_add_u32 s34, s78, s34
	s_addc_u32 s35, s79, s35
	s_and_b64 s[42:43], s[6:7], exec
	s_cselect_b32 s25, s35, s41
	s_cselect_b32 s37, s34, s40
	s_add_u32 s38, s38, 0x40080
	s_addc_u32 s39, s39, 0
	s_add_u32 s59, s40, 0x100
	v_mov_b32_e32 v2, 0
	s_addc_u32 s60, s41, 0
	s_mov_b32 s61, -2
	v_mov_b32_e32 v3, 0
	v_mov_b64_e32 v[4:5], 0
	v_mov_b64_e32 v[6:7], 0
	v_mov_b64_e32 v[8:9], 0
	v_mov_b64_e32 v[18:19], 0
	v_mov_b64_e32 v[20:21], 0
	v_mov_b64_e32 v[22:23], 0
	v_mov_b64_e32 v[24:25], 0
	v_mov_b64_e32 v[34:35], 0
	v_mov_b64_e32 v[36:37], 0
	v_mov_b64_e32 v[38:39], 0
	v_mov_b64_e32 v[40:41], 0
	v_mov_b64_e32 v[50:51], 0
	v_mov_b64_e32 v[52:53], 0
	v_mov_b64_e32 v[54:55], 0
	v_mov_b64_e32 v[56:57], 0
	v_mov_b64_e32 v[10:11], 0
	v_mov_b64_e32 v[12:13], 0
	v_mov_b64_e32 v[14:15], 0
	v_mov_b64_e32 v[16:17], 0
	v_mov_b64_e32 v[26:27], 0
	v_mov_b64_e32 v[28:29], 0
	v_mov_b64_e32 v[30:31], 0
	v_mov_b64_e32 v[32:33], 0
	v_mov_b64_e32 v[42:43], 0
	v_mov_b64_e32 v[44:45], 0
	v_mov_b64_e32 v[46:47], 0
	v_mov_b64_e32 v[48:49], 0
	v_mov_b64_e32 v[58:59], 0
	v_mov_b64_e32 v[60:61], 0
	v_mov_b64_e32 v[62:63], 0
	v_mov_b64_e32 v[64:65], 0
	v_mov_b64_e32 v[66:67], 0
	v_mov_b64_e32 v[68:69], 0
	v_mov_b64_e32 v[70:71], 0
	v_mov_b64_e32 v[72:73], 0
	v_mov_b64_e32 v[82:83], 0
	v_mov_b64_e32 v[84:85], 0
	v_mov_b64_e32 v[86:87], 0
	v_mov_b64_e32 v[88:89], 0
	v_mov_b64_e32 v[98:99], 0
	v_mov_b64_e32 v[100:101], 0
	v_mov_b64_e32 v[102:103], 0
	v_mov_b64_e32 v[104:105], 0
	v_mov_b64_e32 v[114:115], 0
	v_mov_b64_e32 v[116:117], 0
	v_mov_b64_e32 v[118:119], 0
	v_mov_b64_e32 v[120:121], 0
	v_mov_b64_e32 v[74:75], 0
	v_mov_b64_e32 v[76:77], 0
	v_mov_b64_e32 v[78:79], 0
	v_mov_b64_e32 v[80:81], 0
	v_mov_b64_e32 v[90:91], 0
	v_mov_b64_e32 v[92:93], 0
	v_mov_b64_e32 v[94:95], 0
	v_mov_b64_e32 v[96:97], 0
	v_mov_b64_e32 v[106:107], 0
	v_mov_b64_e32 v[108:109], 0
	v_mov_b64_e32 v[110:111], 0
	v_mov_b64_e32 v[112:113], 0
	v_mov_b64_e32 v[122:123], 0
	v_mov_b64_e32 v[124:125], 0
	v_mov_b64_e32 v[126:127], 0
	v_mov_b64_e32 v[128:129], 0

; #define PG8_STAGE(bufoff, gbase, voff) do { _Pragma("unroll") for (int _i = 0; _i < 2; ++_i) \
;         __builtin_amdgcn_global_load_lds((const unsigned*)((const char*)(gbase) + (voff)[_i]), (PG8_LAS unsigned*)(lds + (bufoff) + ldsw + _i * 8192), 16, 0, 0); } while (0)
; #define PG8_LDA(dst, b, h) do { _Pragma("unroll") for (int m = 0; m < 4; ++m) _Pragma("unroll") for (int k = 0; k < 2; ++k) dst[m][k] = *(const PG8_LAS bf16x8*)(lds + PG8_SA(b, h) + aoff + m * 2048 + k * 1024); } while (0)
; #define PG8_LDB(dst, b, h) do { _Pragma("unroll") for (int n = 0; n < 2; ++n) _Pragma("unroll") for (int k = 0; k < 2; ++k) dst[n][k] = *(const PG8_LAS bf16x8*)(lds + PG8_SB(b, h) + boff + n * 2048 + k * 1024); } while (0)
; #define PG8_MMA(ai, bj, At, Bt) do { __builtin_amdgcn_s_setprio(1); _Pragma("unroll") for (int m = 0; m < 4; ++m) _Pragma("unroll") for (int n = 0; n < 2; ++n) _Pragma("unroll") for (int k = 0; k < 2; ++k) \
;         acc[ai][bj][m][n] = __builtin_amdgcn_mfma_f32_16x16x32_bf16(Bt[n][k], At[m][k], acc[ai][bj][m][n], 0, 0, 0); __builtin_amdgcn_s_setprio(0); } while (0)
; #define PG8_WAIT_V(n) asm volatile("s_waitcnt vmcnt(" #n ")" ::: "memory")
; #define PG8_WAIT_L(n) asm volatile("s_waitcnt lgkmcnt(" #n ")" ::: "memory")
; #define PG8_BAR __builtin_amdgcn_s_barrier()
; #define PG8_SCHED __builtin_amdgcn_sched_barrier(0)
; template <class Epi, class Sched, bool ALIGN_EPI = false, bool SP2 = false>
; __device__ __forceinline__ void gemm_phase(PG8_LAS unsigned char* lds, const Gemm g, const Sched& S, const Epi& E) {
;     ...
;             const bool last = (t == nt - 2);
;             const char* a1 = cA + (size_t)(t + 1) * kstep;
;             const char* a2 = last ? nA : cA + (size_t)(t + 2) * kstep; const char* b2 = last ? nB : cB + (size_t)(t + 2) * kstep;
;             const char* a3 = a2 + kstep; const char* b3 = b2 + kstep;
;             if (last && has_next) S.a_ready(nxt);
;             if constexpr (SP2) {
;             PG8_LDB(B0, 0, 0); PG8_LDB(B1, 0, 1); PG8_SCHED; PG8_LDA(At, 0, 0); PG8_STAGE(PG8_SA(1, 1), a1 + hstep, voffA);
;             PG8_WAIT_V(8); PG8_WAIT_L(0); PG8_BAR; PG8_MMA(0, 0, At, B0); PG8_MMA(0, 1, At, B1); PG8_BAR; PG8_SCHED;
;             PG8_LDA(At, 0, 1); PG8_STAGE(PG8_SB(0, 0), b2, voffB); PG8_STAGE(PG8_SB(0, 1), b2 + hstepB, voffB); PG8_STAGE(PG8_SA(0, 0), a2, voffA);
.LBB0_1429:
	v_add_u32_e32 v164, s43, v150
	v_add_u32_e32 v180, s44, v150
	s_add_u32 s26, s8, s24
	ds_read_b128 v[152:155], v164
	ds_read_b128 v[156:159], v164 offset:1024
	ds_read_b128 v[160:163], v164 offset:2048
	ds_read_b128 v[164:167], v164 offset:3072
	ds_read_b128 v[168:171], v180
	ds_read_b128 v[172:175], v180 offset:1024
	ds_read_b128 v[176:179], v180 offset:2048
	ds_read_b128 v[180:183], v180 offset:3072
	s_addc_u32 s27, s9, s25
	s_add_u32 s26, s26, 0x100
	s_addc_u32 s27, s27, 0
	s_add_u32 s55, s21, s24
	s_addc_u32 s56, s45, s25
	s_cmpk_eq_i32 s24, 0x1f00
	s_cselect_b32 s29, s17, s27
	s_cselect_b32 s28, s46, s26
	s_cselect_b32 s27, s15, s56
	s_cselect_b32 s26, s47, s55
	v_lshl_add_u64 v[212:213], v[146:147], 0, s[24:25]
	s_add_i32 m0, s35, 0xc000
	ds_read_b128 v[184:187], v151
	ds_read_b128 v[188:191], v151 offset:1024
	ds_read_b128 v[192:195], v151 offset:2048
	ds_read_b128 v[196:199], v151 offset:3072
	ds_read_b128 v[200:203], v151 offset:4096
	ds_read_b128 v[204:207], v151 offset:5120
	ds_read_b128 v[208:211], v151 offset:6144
	ds_read_b128 v[218:221], v151 offset:7168
	global_load_lds_dwordx4 v[212:213], off
	v_lshl_add_u64 v[212:213], v[148:149], 0, s[24:25]
	s_add_i32 m0, s35, 0xe000
	s_nop 0
	global_load_lds_dwordx4 v[212:213], off
	s_waitcnt vmcnt(8)
	s_waitcnt lgkmcnt(0)
	s_barrier
	v_mfma_f32_16x16x32_bf16 v[126:129], v[152:155], v[184:187], v[126:129]
	v_mfma_f32_16x16x32_bf16 v[122:125], v[160:163], v[184:187], v[122:125]
	v_mfma_f32_16x16x32_bf16 v[110:113], v[152:155], v[192:195], v[110:113]
	v_mfma_f32_16x16x32_bf16 v[106:109], v[160:163], v[192:195], v[106:109]
	v_mfma_f32_16x16x32_bf16 v[94:97], v[152:155], v[200:203], v[94:97]
	v_mfma_f32_16x16x32_bf16 v[90:93], v[160:163], v[200:203], v[90:93]
	v_mfma_f32_16x16x32_bf16 v[78:81], v[152:155], v[208:211], v[78:81]
	v_mfma_f32_16x16x32_bf16 v[74:77], v[160:163], v[208:211], v[74:77]
	v_mfma_f32_16x16x32_bf16 v[126:129], v[156:159], v[188:191], v[126:129]
	v_mfma_f32_16x16x32_bf16 v[122:125], v[164:167], v[188:191], v[122:125]
	v_mfma_f32_16x16x32_bf16 v[110:113], v[156:159], v[196:199], v[110:113]
	v_mfma_f32_16x16x32_bf16 v[106:109], v[164:167], v[196:199], v[106:109]
	v_mfma_f32_16x16x32_bf16 v[94:97], v[156:159], v[204:207], v[94:97]
	v_mfma_f32_16x16x32_bf16 v[90:93], v[164:167], v[204:207], v[90:93]
	v_mfma_f32_16x16x32_bf16 v[78:81], v[156:159], v[218:221], v[78:81]
	v_mfma_f32_16x16x32_bf16 v[74:77], v[164:167], v[218:221], v[74:77]
	v_mfma_f32_16x16x32_bf16 v[118:121], v[168:171], v[184:187], v[118:121]
	v_mfma_f32_16x16x32_bf16 v[114:117], v[176:179], v[184:187], v[114:117]
	v_mfma_f32_16x16x32_bf16 v[102:105], v[168:171], v[192:195], v[102:105]
	v_mfma_f32_16x16x32_bf16 v[98:101], v[176:179], v[192:195], v[98:101]
	v_mfma_f32_16x16x32_bf16 v[86:89], v[168:171], v[200:203], v[86:89]
	v_mfma_f32_16x16x32_bf16 v[82:85], v[176:179], v[200:203], v[82:85]
	v_mfma_f32_16x16x32_bf16 v[70:73], v[168:171], v[208:211], v[70:73]
	v_mfma_f32_16x16x32_bf16 v[66:69], v[176:179], v[208:211], v[66:69]
	v_mfma_f32_16x16x32_bf16 v[118:121], v[172:175], v[188:191], v[118:121]
	v_mfma_f32_16x16x32_bf16 v[114:117], v[180:183], v[188:191], v[114:117]
	v_mfma_f32_16x16x32_bf16 v[102:105], v[172:175], v[196:199], v[102:105]
	v_mfma_f32_16x16x32_bf16 v[98:101], v[180:183], v[196:199], v[98:101]
	v_mfma_f32_16x16x32_bf16 v[86:89], v[172:175], v[204:207], v[86:89]
	v_mfma_f32_16x16x32_bf16 v[82:85], v[180:183], v[204:207], v[82:85]
	v_mfma_f32_16x16x32_bf16 v[70:73], v[172:175], v[218:221], v[70:73]
	v_mfma_f32_16x16x32_bf16 v[66:69], v[180:183], v[218:221], v[66:69]
	s_barrier
	s_add_i32 s55, s43, s34
	v_lshl_add_u64 v[212:213], s[26:27], 0, v[132:133]
	s_mov_b32 m0, s55
	ds_read_b128 v[184:187], v151 offset:16384
	ds_read_b128 v[188:191], v151 offset:17408
	ds_read_b128 v[192:195], v151 offset:18432
	ds_read_b128 v[196:199], v151 offset:19456
	ds_read_b128 v[200:203], v151 offset:20480
	ds_read_b128 v[204:207], v151 offset:21504
	ds_read_b128 v[208:211], v151 offset:22528
	ds_read_b128 v[218:221], v151 offset:23552
	global_load_lds_dwordx4 v[212:213], off
	s_add_i32 m0, s55, 0x2000
	s_add_u32 s56, s26, 0x40000
	v_lshl_add_u64 v[222:223], s[26:27], 0, v[136:137]
	s_addc_u32 s57, s27, 0
	s_add_i32 s55, s44, s34
	global_load_lds_dwordx4 v[222:223], off
	v_lshl_add_u64 v[224:225], s[56:57], 0, v[132:133]
	s_mov_b32 m0, s55
	v_lshl_add_u64 v[226:227], s[28:29], 0, v[134:135]
	global_load_lds_dwordx4 v[224:225], off
	v_lshl_add_u64 v[224:225], s[56:57], 0, v[136:137]
	s_add_i32 m0, s55, 0x2000
	s_nop 0
	global_load_lds_dwordx4 v[224:225], off
	v_lshl_add_u64 v[224:225], s[28:29], 0, v[130:131]
	s_mov_b32 m0, s35
	s_nop 0
	global_load_lds_dwordx4 v[224:225], off
	s_mov_b32 m0, s36
	s_nop 0
	global_load_lds_dwordx4 v[226:227], off
	s_waitcnt vmcnt(8)
	s_waitcnt lgkmcnt(0)
	s_barrier
; #define PG8_STAGE(bufoff, gbase, voff) do { _Pragma("unroll") for (int _i = 0; _i < 2; ++_i) \
;         __builtin_amdgcn_global_load_lds((const unsigned*)((const char*)(gbase) + (voff)[_i]), (PG8_LAS unsigned*)(lds + (bufoff) + ldsw + _i * 8192), 16, 0, 0); } while (0)
; #define PG8_LDA(dst, b, h) do { _Pragma("unroll") for (int m = 0; m < 4; ++m) _Pragma("unroll") for (int k = 0; k < 2; ++k) dst[m][k] = *(const PG8_LAS bf16x8*)(lds + PG8_SA(b, h) + aoff + m * 2048 + k * 1024); } while (0)
; #define PG8_LDB(dst, b, h) do { _Pragma("unroll") for (int n = 0; n < 2; ++n) _Pragma("unroll") for (int k = 0; k < 2; ++k) dst[n][k] = *(const PG8_LAS bf16x8*)(lds + PG8_SB(b, h) + boff + n * 2048 + k * 1024); } while (0)
; #define PG8_MMA(ai, bj, At, Bt) do { __builtin_amdgcn_s_setprio(1); _Pragma("unroll") for (int m = 0; m < 4; ++m) _Pragma("unroll") for (int n = 0; n < 2; ++n) _Pragma("unroll") for (int k = 0; k < 2; ++k) \
;         acc[ai][bj][m][n] = __builtin_amdgcn_mfma_f32_16x16x32_bf16(Bt[n][k], At[m][k], acc[ai][bj][m][n], 0, 0, 0); __builtin_amdgcn_s_setprio(0); } while (0)
; #define PG8_WAIT_V(n) asm volatile("s_waitcnt vmcnt(" #n ")" ::: "memory")
; #define PG8_WAIT_L(n) asm volatile("s_waitcnt lgkmcnt(" #n ")" ::: "memory")
; #define PG8_BAR __builtin_amdgcn_s_barrier()
; #define PG8_SCHED __builtin_amdgcn_sched_barrier(0)
; template <class Epi, class Sched, bool ALIGN_EPI = false, bool SP2 = false>
; __device__ __forceinline__ void gemm_phase(PG8_LAS unsigned char* lds, const Gemm g, const Sched& S, const Epi& E) {
;     ...
;             PG8_WAIT_V(8); PG8_WAIT_L(0); PG8_BAR; PG8_MMA(1, 0, At, B0); PG8_MMA(1, 1, At, B1); PG8_BAR; PG8_SCHED;
;             PG8_LDB(B0, 1, 0); PG8_LDB(B1, 1, 1); PG8_SCHED; PG8_LDA(At, 1, 0); PG8_STAGE(PG8_SA(0, 1), a2 + hstep, voffA);
;             PG8_WAIT_V(8); PG8_WAIT_L(0); PG8_BAR; PG8_MMA(0, 0, At, B0); PG8_MMA(0, 1, At, B1); PG8_BAR; PG8_SCHED;
	v_mfma_f32_16x16x32_bf16 v[62:65], v[152:155], v[184:187], v[62:65]
	v_mfma_f32_16x16x32_bf16 v[58:61], v[160:163], v[184:187], v[58:61]
	v_mfma_f32_16x16x32_bf16 v[46:49], v[152:155], v[192:195], v[46:49]
	v_mfma_f32_16x16x32_bf16 v[42:45], v[160:163], v[192:195], v[42:45]
	v_mfma_f32_16x16x32_bf16 v[30:33], v[152:155], v[200:203], v[30:33]
	v_mfma_f32_16x16x32_bf16 v[26:29], v[160:163], v[200:203], v[26:29]
	v_mfma_f32_16x16x32_bf16 v[14:17], v[152:155], v[208:211], v[14:17]
	v_mfma_f32_16x16x32_bf16 v[10:13], v[160:163], v[208:211], v[10:13]
	v_mfma_f32_16x16x32_bf16 v[62:65], v[156:159], v[188:191], v[62:65]
	v_mfma_f32_16x16x32_bf16 v[58:61], v[164:167], v[188:191], v[58:61]
	v_mfma_f32_16x16x32_bf16 v[46:49], v[156:159], v[196:199], v[46:49]
	v_mfma_f32_16x16x32_bf16 v[42:45], v[164:167], v[196:199], v[42:45]
	v_mfma_f32_16x16x32_bf16 v[30:33], v[156:159], v[204:207], v[30:33]
	v_mfma_f32_16x16x32_bf16 v[26:29], v[164:167], v[204:207], v[26:29]
	v_mfma_f32_16x16x32_bf16 v[14:17], v[156:159], v[218:221], v[14:17]
	v_mfma_f32_16x16x32_bf16 v[10:13], v[164:167], v[218:221], v[10:13]
	v_mfma_f32_16x16x32_bf16 v[54:57], v[168:171], v[184:187], v[54:57]
	v_mfma_f32_16x16x32_bf16 v[50:53], v[176:179], v[184:187], v[50:53]
	v_mfma_f32_16x16x32_bf16 v[38:41], v[168:171], v[192:195], v[38:41]
	v_mfma_f32_16x16x32_bf16 v[34:37], v[176:179], v[192:195], v[34:37]
	v_mfma_f32_16x16x32_bf16 v[22:25], v[168:171], v[200:203], v[22:25]
	v_mfma_f32_16x16x32_bf16 v[18:21], v[176:179], v[200:203], v[18:21]
	v_mfma_f32_16x16x32_bf16 v[6:9], v[168:171], v[208:211], v[6:9]
	v_mfma_f32_16x16x32_bf16 v[2:5], v[176:179], v[208:211], v[2:5]
	v_mfma_f32_16x16x32_bf16 v[54:57], v[172:175], v[188:191], v[54:57]
	v_mfma_f32_16x16x32_bf16 v[50:53], v[180:183], v[188:191], v[50:53]
	v_mfma_f32_16x16x32_bf16 v[38:41], v[172:175], v[196:199], v[38:41]
	v_mfma_f32_16x16x32_bf16 v[34:37], v[180:183], v[196:199], v[34:37]
	v_mfma_f32_16x16x32_bf16 v[22:25], v[172:175], v[204:207], v[22:25]
	v_mfma_f32_16x16x32_bf16 v[18:21], v[180:183], v[204:207], v[18:21]
	v_mfma_f32_16x16x32_bf16 v[6:9], v[172:175], v[218:221], v[6:9]
	v_mfma_f32_16x16x32_bf16 v[2:5], v[180:183], v[218:221], v[2:5]
	s_barrier
	s_add_i32 s55, 0, 0x18000
	s_add_i32 s56, 0, 0x1c000
	v_add_u32_e32 v164, s55, v150
	v_add_u32_e32 v180, s56, v150
	ds_read_b128 v[152:155], v164
	ds_read_b128 v[156:159], v164 offset:1024
	ds_read_b128 v[160:163], v164 offset:2048
	ds_read_b128 v[164:167], v164 offset:3072
	ds_read_b128 v[168:171], v180
	ds_read_b128 v[172:175], v180 offset:1024
	ds_read_b128 v[176:179], v180 offset:2048
	ds_read_b128 v[180:183], v180 offset:3072
	s_add_u32 s28, s28, 0x100000
	s_addc_u32 s29, s29, 0
	s_mov_b32 m0, s37
	v_lshl_add_u64 v[228:229], s[28:29], 0, v[130:131]
	ds_read_b128 v[184:187], v151 offset:32768
	ds_read_b128 v[188:191], v151 offset:33792
	ds_read_b128 v[192:195], v151 offset:34816
	ds_read_b128 v[196:199], v151 offset:35840
	ds_read_b128 v[200:203], v151 offset:36864
	ds_read_b128 v[204:207], v151 offset:37888
	ds_read_b128 v[208:211], v151 offset:38912
	ds_read_b128 v[218:221], v151 offset:39936
	global_load_lds_dwordx4 v[228:229], off
	v_lshl_add_u64 v[228:229], s[28:29], 0, v[134:135]
	s_mov_b32 m0, s39
	s_nop 0
	global_load_lds_dwordx4 v[228:229], off
	s_waitcnt vmcnt(8)
	s_waitcnt lgkmcnt(0)
	s_barrier
	v_mfma_f32_16x16x32_bf16 v[126:129], v[152:155], v[184:187], v[126:129]
	v_mfma_f32_16x16x32_bf16 v[122:125], v[160:163], v[184:187], v[122:125]
	v_mfma_f32_16x16x32_bf16 v[110:113], v[152:155], v[192:195], v[110:113]
	v_mfma_f32_16x16x32_bf16 v[106:109], v[160:163], v[192:195], v[106:109]
	v_mfma_f32_16x16x32_bf16 v[94:97], v[152:155], v[200:203], v[94:97]
	v_mfma_f32_16x16x32_bf16 v[90:93], v[160:163], v[200:203], v[90:93]
	v_mfma_f32_16x16x32_bf16 v[78:81], v[152:155], v[208:211], v[78:81]
	v_mfma_f32_16x16x32_bf16 v[74:77], v[160:163], v[208:211], v[74:77]
	v_mfma_f32_16x16x32_bf16 v[126:129], v[156:159], v[188:191], v[126:129]
	v_mfma_f32_16x16x32_bf16 v[122:125], v[164:167], v[188:191], v[122:125]
	v_mfma_f32_16x16x32_bf16 v[110:113], v[156:159], v[196:199], v[110:113]
	v_mfma_f32_16x16x32_bf16 v[106:109], v[164:167], v[196:199], v[106:109]
	v_mfma_f32_16x16x32_bf16 v[94:97], v[156:159], v[204:207], v[94:97]
	v_mfma_f32_16x16x32_bf16 v[90:93], v[164:167], v[204:207], v[90:93]
	v_mfma_f32_16x16x32_bf16 v[78:81], v[156:159], v[218:221], v[78:81]
	v_mfma_f32_16x16x32_bf16 v[74:77], v[164:167], v[218:221], v[74:77]
	v_mfma_f32_16x16x32_bf16 v[118:121], v[168:171], v[184:187], v[118:121]
	v_mfma_f32_16x16x32_bf16 v[114:117], v[176:179], v[184:187], v[114:117]
	v_mfma_f32_16x16x32_bf16 v[102:105], v[168:171], v[192:195], v[102:105]
	v_mfma_f32_16x16x32_bf16 v[98:101], v[176:179], v[192:195], v[98:101]
	v_mfma_f32_16x16x32_bf16 v[86:89], v[168:171], v[200:203], v[86:89]
	v_mfma_f32_16x16x32_bf16 v[82:85], v[176:179], v[200:203], v[82:85]
	v_mfma_f32_16x16x32_bf16 v[70:73], v[168:171], v[208:211], v[70:73]
	v_mfma_f32_16x16x32_bf16 v[66:69], v[176:179], v[208:211], v[66:69]
	v_mfma_f32_16x16x32_bf16 v[118:121], v[172:175], v[188:191], v[118:121]
	v_mfma_f32_16x16x32_bf16 v[114:117], v[180:183], v[188:191], v[114:117]
	v_mfma_f32_16x16x32_bf16 v[102:105], v[172:175], v[196:199], v[102:105]
	v_mfma_f32_16x16x32_bf16 v[98:101], v[180:183], v[196:199], v[98:101]
	v_mfma_f32_16x16x32_bf16 v[86:89], v[172:175], v[204:207], v[86:89]
	v_mfma_f32_16x16x32_bf16 v[82:85], v[180:183], v[204:207], v[82:85]
	v_mfma_f32_16x16x32_bf16 v[70:73], v[172:175], v[218:221], v[70:73]
	v_mfma_f32_16x16x32_bf16 v[66:69], v[180:183], v[218:221], v[66:69]
	s_barrier
; #define PG8_STAGE(bufoff, gbase, voff) do { _Pragma("unroll") for (int _i = 0; _i < 2; ++_i) \
;         __builtin_amdgcn_global_load_lds((const unsigned*)((const char*)(gbase) + (voff)[_i]), (PG8_LAS unsigned*)(lds + (bufoff) + ldsw + _i * 8192), 16, 0, 0); } while (0)
; #define PG8_LDA(dst, b, h) do { _Pragma("unroll") for (int m = 0; m < 4; ++m) _Pragma("unroll") for (int k = 0; k < 2; ++k) dst[m][k] = *(const PG8_LAS bf16x8*)(lds + PG8_SA(b, h) + aoff + m * 2048 + k * 1024); } while (0)
; #define PG8_MMA(ai, bj, At, Bt) do { __builtin_amdgcn_s_setprio(1); _Pragma("unroll") for (int m = 0; m < 4; ++m) _Pragma("unroll") for (int n = 0; n < 2; ++n) _Pragma("unroll") for (int k = 0; k < 2; ++k) \
;         acc[ai][bj][m][n] = __builtin_amdgcn_mfma_f32_16x16x32_bf16(Bt[n][k], At[m][k], acc[ai][bj][m][n], 0, 0, 0); __builtin_amdgcn_s_setprio(0); } while (0)
; #define PG8_WAIT_V(n) asm volatile("s_waitcnt vmcnt(" #n ")" ::: "memory")
; #define PG8_WAIT_L(n) asm volatile("s_waitcnt lgkmcnt(" #n ")" ::: "memory")
; #define PG8_BAR __builtin_amdgcn_s_barrier()
; #define PG8_SCHED __builtin_amdgcn_sched_barrier(0)
; template <class Epi, class Sched, bool ALIGN_EPI = false, bool SP2 = false>
; __device__ __forceinline__ void gemm_phase(PG8_LAS unsigned char* lds, const Gemm g, const Sched& S, const Epi& E) {
;     ...
;             PG8_LDA(At, 1, 1); PG8_STAGE(PG8_SB(1, 0), b3, voffB); PG8_STAGE(PG8_SB(1, 1), b3 + hstepB, voffB); PG8_STAGE(PG8_SA(1, 0), a3, voffA);
;             PG8_WAIT_V(8); PG8_WAIT_L(0); PG8_BAR; PG8_MMA(1, 0, At, B0); PG8_MMA(1, 1, At, B1); PG8_BAR; PG8_SCHED;
;     ...
; #pragma unroll
;         for (int a = 0; a < 2; ++a)
; #pragma unroll
;             for (int b = 0; b < 2; ++b)
; #pragma unroll
;                 for (int m = 0; m < 4; ++m)
; #pragma unroll
;                     for (int n = 0; n < 2; ++n) acc[a][b][m][n] = (f32x4){0.f, 0.f, 0.f, 0.f};
	s_add_i32 s28, s55, s34
	v_lshl_add_u64 v[212:213], v[212:213], 0, s[10:11]
	s_mov_b32 m0, s28
	ds_read_b128 v[184:187], v151 offset:49152
	ds_read_b128 v[188:191], v151 offset:50176
	ds_read_b128 v[192:195], v151 offset:51200
	ds_read_b128 v[196:199], v151 offset:52224
	ds_read_b128 v[200:203], v151 offset:53248
	ds_read_b128 v[204:207], v151 offset:54272
	ds_read_b128 v[208:211], v151 offset:55296
	ds_read_b128 v[218:221], v151 offset:56320
	global_load_lds_dwordx4 v[212:213], off
	s_add_i32 m0, s28, 0x2000
	s_add_u32 s26, s26, 0x40080
	v_lshl_add_u64 v[212:213], v[222:223], 0, s[10:11]
	s_addc_u32 s27, s27, 0
	s_add_i32 s28, s56, s34
	global_load_lds_dwordx4 v[212:213], off
	v_lshl_add_u64 v[212:213], s[26:27], 0, v[132:133]
	s_mov_b32 m0, s28
	s_nop 0
	global_load_lds_dwordx4 v[212:213], off
	v_lshl_add_u64 v[212:213], s[26:27], 0, v[136:137]
	s_add_i32 m0, s28, 0x2000
	s_nop 0
	global_load_lds_dwordx4 v[212:213], off
	v_lshl_add_u64 v[212:213], v[224:225], 0, s[10:11]
	s_mov_b32 m0, s40
	s_nop 0
	global_load_lds_dwordx4 v[212:213], off
	v_lshl_add_u64 v[212:213], v[226:227], 0, s[10:11]
	s_mov_b32 m0, s41
	s_nop 0
	global_load_lds_dwordx4 v[212:213], off
	s_waitcnt vmcnt(8)
	s_waitcnt lgkmcnt(0)
	s_barrier
	v_mfma_f32_16x16x32_bf16 v[62:65], v[152:155], v[184:187], v[62:65]
	v_mfma_f32_16x16x32_bf16 v[58:61], v[160:163], v[184:187], v[58:61]
	v_mfma_f32_16x16x32_bf16 v[46:49], v[152:155], v[192:195], v[46:49]
	v_mfma_f32_16x16x32_bf16 v[42:45], v[160:163], v[192:195], v[42:45]
	v_mfma_f32_16x16x32_bf16 v[30:33], v[152:155], v[200:203], v[30:33]
	v_mfma_f32_16x16x32_bf16 v[26:29], v[160:163], v[200:203], v[26:29]
	v_mfma_f32_16x16x32_bf16 v[14:17], v[152:155], v[208:211], v[14:17]
	v_mfma_f32_16x16x32_bf16 v[10:13], v[160:163], v[208:211], v[10:13]
	v_mfma_f32_16x16x32_bf16 v[62:65], v[156:159], v[188:191], v[62:65]
	v_mfma_f32_16x16x32_bf16 v[58:61], v[164:167], v[188:191], v[58:61]
	v_mfma_f32_16x16x32_bf16 v[46:49], v[156:159], v[196:199], v[46:49]
	v_mfma_f32_16x16x32_bf16 v[42:45], v[164:167], v[196:199], v[42:45]
	v_mfma_f32_16x16x32_bf16 v[30:33], v[156:159], v[204:207], v[30:33]
	v_mfma_f32_16x16x32_bf16 v[26:29], v[164:167], v[204:207], v[26:29]
	v_mfma_f32_16x16x32_bf16 v[14:17], v[156:159], v[218:221], v[14:17]
	v_mfma_f32_16x16x32_bf16 v[10:13], v[164:167], v[218:221], v[10:13]
	v_mfma_f32_16x16x32_bf16 v[54:57], v[168:171], v[184:187], v[54:57]
	v_mfma_f32_16x16x32_bf16 v[50:53], v[176:179], v[184:187], v[50:53]
	v_mfma_f32_16x16x32_bf16 v[38:41], v[168:171], v[192:195], v[38:41]
	v_mfma_f32_16x16x32_bf16 v[34:37], v[176:179], v[192:195], v[34:37]
	v_mfma_f32_16x16x32_bf16 v[22:25], v[168:171], v[200:203], v[22:25]
	v_mfma_f32_16x16x32_bf16 v[18:21], v[176:179], v[200:203], v[18:21]
	v_mfma_f32_16x16x32_bf16 v[6:9], v[168:171], v[208:211], v[6:9]
	v_mfma_f32_16x16x32_bf16 v[2:5], v[176:179], v[208:211], v[2:5]
	v_mfma_f32_16x16x32_bf16 v[54:57], v[172:175], v[188:191], v[54:57]
	v_mfma_f32_16x16x32_bf16 v[50:53], v[180:183], v[188:191], v[50:53]
	v_mfma_f32_16x16x32_bf16 v[38:41], v[172:175], v[196:199], v[38:41]
	v_mfma_f32_16x16x32_bf16 v[34:37], v[180:183], v[196:199], v[34:37]
	v_mfma_f32_16x16x32_bf16 v[22:25], v[172:175], v[204:207], v[22:25]
	v_mfma_f32_16x16x32_bf16 v[18:21], v[180:183], v[204:207], v[18:21]
	v_mfma_f32_16x16x32_bf16 v[6:9], v[172:175], v[218:221], v[6:9]
	v_mfma_f32_16x16x32_bf16 v[2:5], v[180:183], v[218:221], v[2:5]
	s_barrier
	s_add_i32 s54, s54, 2
	s_add_u32 s24, s24, 0x100
	s_addc_u32 s25, s25, 0
	s_cmp_gt_u32 s54, 61
	s_cbranch_scc0 .LBB0_1429
	s_add_u32 s24, s21, 0xffffff00
	s_addc_u32 s25, s45, -1
	s_andn2_b64 vcc, exec, s[2:3]
	s_cbranch_vccnz .LBB0_1420
	v_mov_b32_e32 v2, 0
	s_mov_b32 s6, s14
	s_mov_b32 s4, s16
	s_mov_b64 s[8:9], s[22:23]
	s_mov_b32 s42, s20
	v_mov_b32_e32 v3, 0
	v_mov_b64_e32 v[4:5], 0
	v_mov_b64_e32 v[6:7], 0
	v_mov_b64_e32 v[8:9], 0
	v_mov_b64_e32 v[18:19], 0
	v_mov_b64_e32 v[20:21], 0
	v_mov_b64_e32 v[22:23], 0
	v_mov_b64_e32 v[24:25], 0
	v_mov_b64_e32 v[34:35], 0
	v_mov_b64_e32 v[36:37], 0
	v_mov_b64_e32 v[38:39], 0
	v_mov_b64_e32 v[40:41], 0
	v_mov_b64_e32 v[50:51], 0
	v_mov_b64_e32 v[52:53], 0
	v_mov_b64_e32 v[54:55], 0
	v_mov_b64_e32 v[56:57], 0
	v_mov_b64_e32 v[10:11], 0
	v_mov_b64_e32 v[12:13], 0
	v_mov_b64_e32 v[14:15], 0
	v_mov_b64_e32 v[16:17], 0
	v_mov_b64_e32 v[26:27], 0
	v_mov_b64_e32 v[28:29], 0
	v_mov_b64_e32 v[30:31], 0
	v_mov_b64_e32 v[32:33], 0
	v_mov_b64_e32 v[42:43], 0
	v_mov_b64_e32 v[44:45], 0
	v_mov_b64_e32 v[46:47], 0
	v_mov_b64_e32 v[48:49], 0
	v_mov_b64_e32 v[58:59], 0
	v_mov_b64_e32 v[60:61], 0
	v_mov_b64_e32 v[62:63], 0
	v_mov_b64_e32 v[64:65], 0
	v_mov_b64_e32 v[66:67], 0
	v_mov_b64_e32 v[68:69], 0
	v_mov_b64_e32 v[70:71], 0
	v_mov_b64_e32 v[72:73], 0
	v_mov_b64_e32 v[82:83], 0
	v_mov_b64_e32 v[84:85], 0
	v_mov_b64_e32 v[86:87], 0
	v_mov_b64_e32 v[88:89], 0
	v_mov_b64_e32 v[98:99], 0
	v_mov_b64_e32 v[100:101], 0
	v_mov_b64_e32 v[102:103], 0
	v_mov_b64_e32 v[104:105], 0
	v_mov_b64_e32 v[114:115], 0
	v_mov_b64_e32 v[116:117], 0
	v_mov_b64_e32 v[118:119], 0
	v_mov_b64_e32 v[120:121], 0
	v_mov_b64_e32 v[74:75], 0
	v_mov_b64_e32 v[76:77], 0
	v_mov_b64_e32 v[78:79], 0
	v_mov_b64_e32 v[80:81], 0
	v_mov_b64_e32 v[90:91], 0
	v_mov_b64_e32 v[92:93], 0
	v_mov_b64_e32 v[94:95], 0
	v_mov_b64_e32 v[96:97], 0
	v_mov_b64_e32 v[106:107], 0
	v_mov_b64_e32 v[108:109], 0
	v_mov_b64_e32 v[110:111], 0
	v_mov_b64_e32 v[112:113], 0
	v_mov_b64_e32 v[122:123], 0
	v_mov_b64_e32 v[124:125], 0
	v_mov_b64_e32 v[126:127], 0
	v_mov_b64_e32 v[128:129], 0
	s_andn2_b64 vcc, exec, s[0:1]
	s_cbranch_vccnz .LBB0_1421
